# RET step region pipelined + distributed L2 prefetch of next-next Q/K chunk (1 dword load per CU per step) + ph0 grid.sync replaced by the xcd barrier
# speedup vs baseline: 1.0001x; 1.0001x over previous
; #define LAS __attribute__((address_space(3)))
; DI void ret_chain_phase(const Ctx& a, LAS unsigned char* lds) {
;     ...
;         const int qk_src = ((tid >> 5) * 1024 + h * 256 + (((tid & 31) ^ ((tid >> 5) & 15)) * 8)) * 2;
;     ...
;         RC_ISSUE(0);
;         RC_DMA_QK(0);
;         for (int s = 0; s < 68; ++s) {
;             const int row0 = RC_ROW0(s);
; #pragma unroll
;             for (int k = 0; k < 4; ++k) { const int p = tid + k * NTHREADS; const int d = p >> 3, ch = p & 7;
;                 *(LAS u32x4*)(lds + RC_SKT + d * 128 + ((ch ^ ((d >> 1) & 7)) << 4)) = pkt[k]; }
;             { const int v_ = tid >> 3, ch = tid & 7;
;                 *(LAS u32x4*)(lds + RC_SVT + v_ * 128 + ((ch ^ ((v_ >> 1) & 7)) << 4)) = pvt; }
;             asm volatile("s_waitcnt vmcnt(0)" ::: "memory");
;             if (s + 1 < 68) RC_ISSUE(s + 1);
.LBB0_207:
	s_lshl_b32 s20, s51, 6
	s_add_i32 s20, s20, s46
	s_ashr_i32 s20, s20, 6
	s_ashr_i32 s21, s20, 31
	s_lshl_b64 s[46:47], s[20:21], 10
	s_or_b64 s[46:47], s[46:47], s[88:89]
	v_lshl_add_u64 v[32:33], s[46:47], 0, v[90:91]
	v_lshl_add_u64 v[36:37], s[46:47], 0, v[94:95]
	v_lshl_add_u64 v[40:41], s[46:47], 0, v[96:97]
	v_lshl_add_u64 v[44:45], s[46:47], 0, v[98:99]
	v_lshlrev_b64 v[32:33], 7, v[32:33]
	v_lshlrev_b64 v[36:37], 7, v[36:37]
	v_lshlrev_b64 v[40:41], 7, v[40:41]
	v_lshlrev_b64 v[44:45], 7, v[44:45]
	s_lshl_b64 s[20:21], s[20:21], 18
	v_lshl_add_u64 v[32:33], v[114:115], 0, v[32:33]
	v_lshl_add_u64 v[36:37], v[114:115], 0, v[36:37]
	v_lshl_add_u64 v[40:41], v[114:115], 0, v[40:41]
	v_lshl_add_u64 v[44:45], v[114:115], 0, v[44:45]
	v_lshl_add_u64 v[48:49], v[118:119], 0, s[20:21]
	v_mov_b32_e32 v105, v120
	global_load_dwordx4 v[32:35], v[32:33], off
	s_mov_b64 s[46:47], -1
	global_load_dwordx4 v[36:39], v[36:37], off
	s_and_b64 vcc, exec, s[30:31]
	global_load_dwordx4 v[40:43], v[40:41], off
	s_nop 0
	global_load_dwordx4 v[44:47], v[44:45], off
	s_nop 0
	global_load_dwordx4 v[48:51], v[48:49], off
	s_cmp_gt_u32 s45, 65
	s_cbranch_scc1 .Lrc_pf_skip
	v_readfirstlane_b32 s20, v200
	s_nop 3
	s_cmp_lt_u32 s20, 64
	s_cbranch_scc0 .Lrc_pf_skip
	s_cmp_gt_u32 s45, 1
	s_cbranch_scc1 .Lrc_pf_lat
	s_add_i32 s98, s45, 2
	s_sub_i32 s99, s48, 65
	s_cmp_lg_u64 s[42:43], 0
	s_cselect_b32 s98, s98, s99
	s_lshl_b32 s98, s98, 6
	s_add_i32 s98, s98, s37
	s_branch .Lrc_pf_go
.Lrc_pf_lat:
	s_add_i32 s98, s45, -2
	s_add_i32 s99, s48, -1
	s_cmp_lg_u64 s[42:43], 0
	s_cselect_b32 s98, s98, s99
	s_lshl_b32 s98, s98, 6
	s_add_i32 s98, s98, s44
.Lrc_pf_go:
	s_bfe_u32 s99, s3, 0x30003
	s_and_b32 s20, s99, 3
	s_lshl_b32 s20, s20, 4
	s_add_i32 s98, s98, s20
	s_lshl_b32 s98, s98, 11
	s_lshl_b32 s20, s88, 1
	s_add_i32 s98, s98, s20
	s_cmp_lt_u32 s99, 4
	s_cselect_b32 s20, s76, s80
	s_cselect_b32 s21, s77, s81
	v_lshrrev_b32_e32 v251, 2, v200
	v_and_b32_e32 v250, 3, v200
	v_lshlrev_b32_e32 v251, 11, v251
	v_lshl_add_u32 v250, v250, 7, v251
	v_add_u32_e32 v250, s98, v250
	global_load_dword v251, v250, s[20:21]
; #define LAS __attribute__((address_space(3)))
; DI unsigned pk2(float lo, float hi) { const f32x2 v = {lo, hi}; const hbf16x2 b = __builtin_convertvector(v, hbf16x2); return __builtin_bit_cast(unsigned, b); }
; #define LDS_BARRIER() do { asm volatile("s_waitcnt lgkmcnt(0)" ::: "memory"); __builtin_amdgcn_s_barrier(); } while (0)
; #define MFMA16(a, b, c) __builtin_amdgcn_mfma_f32_16x16x32_bf16((a), (b), (c), 0, 0, 0)
; DI void ret_chain_phase(const Ctx& a, LAS unsigned char* lds) {
;     ...
;             int frx = fr; asm volatile("" : "+v"(frx));
;             const int sw5 = frx * 512, sw1 = frx * 128, kx = (frx >> 1) & 7;
;     ...
;             bf16x8 qf[8];
; #pragma unroll
;             for (int ks = 0; ks < 8; ++ks) qf[ks] = *(const LAS bf16x8*)(lds + A512(RC_SQ, it, ks));
; #pragma unroll
;             for (int j2 = 0; j2 < 2; ++j2) {
;                 const int jt = 2 * half + j2;
;                 f32x4 acc = (f32x4){0.f, 0.f, 0.f, 0.f};
; #pragma unroll
;                 for (int ks = 0; ks < 8; ++ks) { const bf16x8 kf = *(const LAS bf16x8*)(lds + A512(RC_SK, jt, ks)); acc = MFMA16(kf, qf[ks], acc); }
;                 float pv[4];
; #pragma unroll
;                 for (int r = 0; r < 4; ++r) pv[r] = acc[r] * wdec[j2][r];
;                 u32x2 w; w.x = pk2(pv[0], pv[1]); w.y = pk2(pv[2], pv[3]);
;                 *(LAS u32x2*)(lds + RC_SP + icol * 128 + (((2 * jt + (fq >> 1)) ^ ((icol >> 1) & 7)) << 4) + (fq & 1) * 8) = w;
;             }
;             f32x4 accO[2];
; #pragma unroll
;             for (int vv = 0; vv < 2; ++vv) {
;                 f32x4 acc = (f32x4){0.f, 0.f, 0.f, 0.f};
; #pragma unroll
;                 for (int ks = 0; ks < 8; ++ks) { const bf16x8 sf = *(const LAS bf16x8*)(lds + A512(RC_SS, 2 * half + vv, ks)); acc = MFMA16(sf, qf[ks], acc); }
;                 accO[vv] = acc * qdec;
;             }
;             LDS_BARRIER();
.Lrc_pf_skip:
	s_waitcnt lgkmcnt(0)
	s_barrier
	s_nop 0
	v_lshlrev_b32_e32 v198, 9, v105
	v_xor_b32_e32 v199, v105, v121
	v_xor_b32_e32 v206, v105, v129
	v_xor_b32_e32 v207, v105, v157
	v_xor_b32_e32 v208, v105, v158
	v_xor_b32_e32 v209, v105, v159
	v_xor_b32_e32 v219, v105, v160
	v_xor_b32_e32 v220, v105, v161
	v_xor_b32_e32 v221, v105, v162
	v_lshlrev_b32_e32 v199, 4, v199
	v_lshlrev_b32_e32 v206, 4, v206
	v_lshlrev_b32_e32 v207, 4, v207
	v_lshlrev_b32_e32 v208, 4, v208
	v_lshlrev_b32_e32 v209, 4, v209
	v_lshlrev_b32_e32 v219, 4, v219
	v_lshlrev_b32_e32 v220, 4, v220
	v_lshlrev_b32_e32 v221, 4, v221
	v_add3_u32 v250, v126, v198, v199
	ds_read_b128 v[76:79], v250
	v_add3_u32 v250, v126, v198, v206
	ds_read_b128 v[80:83], v250
	v_add3_u32 v250, v126, v198, v207
	ds_read_b128 v[72:75], v250
	v_add3_u32 v250, v126, v198, v208
	ds_read_b128 v[68:71], v250
	v_add3_u32 v250, v126, v198, v209
	ds_read_b128 v[64:67], v250
	v_add3_u32 v250, v126, v198, v219
	ds_read_b128 v[60:63], v250
	v_add3_u32 v250, v126, v198, v220
	ds_read_b128 v[56:59], v250
	v_add3_u32 v250, v126, v198, v221
	ds_read_b128 v[52:55], v250
	v_add3_u32 v250, v127, v198, v199
	ds_read_b128 v[194:197], v250 offset:32768
	v_add3_u32 v250, v127, v198, v206
	ds_read_b128 v[230:233], v250 offset:32768
	v_add3_u32 v250, v127, v198, v207
	ds_read_b128 v[234:237], v250 offset:32768
	v_add3_u32 v250, v127, v198, v208
	ds_read_b128 v[238:241], v250 offset:32768
	v_add3_u32 v250, v127, v198, v209
	ds_read_b128 v[242:245], v250 offset:32768
	s_waitcnt lgkmcnt(5)
	s_waitcnt lgkmcnt(4)
	v_mfma_f32_16x16x32_bf16 v[222:225], v[194:197], v[76:79], 0
	v_add3_u32 v250, v127, v198, v219
	ds_read_b128 v[194:197], v250 offset:32768
	s_waitcnt lgkmcnt(4)
	v_mfma_f32_16x16x32_bf16 v[222:225], v[230:233], v[80:83], v[222:225]
	v_add3_u32 v250, v127, v198, v220
	ds_read_b128 v[230:233], v250 offset:32768
	s_waitcnt lgkmcnt(4)
	v_mfma_f32_16x16x32_bf16 v[222:225], v[234:237], v[72:75], v[222:225]
	v_add3_u32 v250, v127, v198, v221
	ds_read_b128 v[234:237], v250 offset:32768
	s_waitcnt lgkmcnt(4)
	v_mfma_f32_16x16x32_bf16 v[222:225], v[238:241], v[68:71], v[222:225]
	v_add3_u32 v250, v163, v198, v199
	ds_read_b128 v[238:241], v250 offset:32768
	s_waitcnt lgkmcnt(4)
	v_mfma_f32_16x16x32_bf16 v[222:225], v[242:245], v[64:67], v[222:225]
	v_add3_u32 v250, v163, v198, v206
	ds_read_b128 v[242:245], v250 offset:32768
	s_waitcnt lgkmcnt(4)
	v_mfma_f32_16x16x32_bf16 v[222:225], v[194:197], v[60:63], v[222:225]
	v_add3_u32 v250, v163, v198, v207
	ds_read_b128 v[194:197], v250 offset:32768
	s_waitcnt lgkmcnt(4)
	v_mfma_f32_16x16x32_bf16 v[222:225], v[230:233], v[56:59], v[222:225]
	v_add3_u32 v250, v163, v198, v208
	ds_read_b128 v[230:233], v250 offset:32768
	s_waitcnt lgkmcnt(4)
	v_mfma_f32_16x16x32_bf16 v[222:225], v[234:237], v[52:55], v[222:225]
	v_add3_u32 v250, v163, v198, v209
	ds_read_b128 v[234:237], v250 offset:32768
	s_waitcnt lgkmcnt(4)
	v_mfma_f32_16x16x32_bf16 v[246:249], v[238:241], v[76:79], 0
	v_add3_u32 v250, v163, v198, v219
	ds_read_b128 v[238:241], v250 offset:32768
	s_waitcnt lgkmcnt(4)
	v_mfma_f32_16x16x32_bf16 v[246:249], v[242:245], v[80:83], v[246:249]
	v_add3_u32 v250, v163, v198, v220
	ds_read_b128 v[242:245], v250 offset:32768
	s_waitcnt lgkmcnt(4)
	v_mfma_f32_16x16x32_bf16 v[246:249], v[194:197], v[72:75], v[246:249]
	v_add3_u32 v250, v163, v198, v221
	ds_read_b128 v[194:197], v250 offset:32768
	s_waitcnt lgkmcnt(4)
	v_mfma_f32_16x16x32_bf16 v[246:249], v[230:233], v[68:71], v[246:249]
	v_add3_u32 v250, v164, v198, v199
	ds_read_b128 v[230:233], v250
	v_mul_f32_e32 v222, v179, v222
	v_mul_f32_e32 v223, v180, v223
	v_mul_f32_e32 v224, v185, v224
	v_mul_f32_e32 v225, v186, v225
	v_cvt_pk_bf16_f32 v222, v222, v223
	v_cvt_pk_bf16_f32 v223, v224, v225
	ds_write_b64 v175, v[222:223]
	s_waitcnt lgkmcnt(5)
	v_mfma_f32_16x16x32_bf16 v[246:249], v[234:237], v[64:67], v[246:249]
	v_add3_u32 v250, v164, v198, v206
	ds_read_b128 v[234:237], v250
	s_waitcnt lgkmcnt(5)
	v_mfma_f32_16x16x32_bf16 v[246:249], v[238:241], v[60:63], v[246:249]
	v_add3_u32 v250, v164, v198, v207
	ds_read_b128 v[238:241], v250
	s_waitcnt lgkmcnt(5)
	v_mfma_f32_16x16x32_bf16 v[246:249], v[242:245], v[56:59], v[246:249]
	v_add3_u32 v250, v164, v198, v208
	ds_read_b128 v[242:245], v250
	s_waitcnt lgkmcnt(5)
	v_mfma_f32_16x16x32_bf16 v[246:249], v[194:197], v[52:55], v[246:249]
	v_add3_u32 v250, v164, v198, v209
	ds_read_b128 v[194:197], v250
	s_waitcnt lgkmcnt(5)
	v_mfma_f32_16x16x32_bf16 v[84:87], v[230:233], v[76:79], 0
	v_add3_u32 v250, v164, v198, v219
	ds_read_b128 v[230:233], v250
	s_waitcnt lgkmcnt(4)
	v_mfma_f32_16x16x32_bf16 v[84:87], v[234:237], v[80:83], v[84:87]
	v_add3_u32 v250, v164, v198, v220
	ds_read_b128 v[234:237], v250
	s_waitcnt lgkmcnt(4)
	v_mfma_f32_16x16x32_bf16 v[84:87], v[238:241], v[72:75], v[84:87]
	v_add3_u32 v250, v164, v198, v221
	ds_read_b128 v[238:241], v250
	s_waitcnt lgkmcnt(4)
	v_mfma_f32_16x16x32_bf16 v[84:87], v[242:245], v[68:71], v[84:87]
	v_add3_u32 v250, v165, v198, v199
	ds_read_b128 v[242:245], v250
	v_mul_f32_e32 v246, v181, v246
	v_mul_f32_e32 v247, v182, v247
	v_mul_f32_e32 v248, v183, v248
	v_mul_f32_e32 v249, v184, v249
	v_cvt_pk_bf16_f32 v246, v246, v247
	v_cvt_pk_bf16_f32 v247, v248, v249
	ds_write_b64 v176, v[246:247]
	s_waitcnt lgkmcnt(5)
	v_mfma_f32_16x16x32_bf16 v[84:87], v[194:197], v[64:67], v[84:87]
	v_add3_u32 v250, v165, v198, v206
	ds_read_b128 v[194:197], v250
	s_waitcnt lgkmcnt(5)
	v_mfma_f32_16x16x32_bf16 v[84:87], v[230:233], v[60:63], v[84:87]
	v_add3_u32 v250, v165, v198, v207
	ds_read_b128 v[230:233], v250
	s_waitcnt lgkmcnt(5)
	v_mfma_f32_16x16x32_bf16 v[84:87], v[234:237], v[56:59], v[84:87]
	v_add3_u32 v250, v165, v198, v208
	ds_read_b128 v[234:237], v250
	s_waitcnt lgkmcnt(5)
	v_mfma_f32_16x16x32_bf16 v[84:87], v[238:241], v[52:55], v[84:87]
	v_add3_u32 v250, v165, v198, v209
	ds_read_b128 v[238:241], v250
	s_waitcnt lgkmcnt(5)
	v_mfma_f32_16x16x32_bf16 v[222:225], v[242:245], v[76:79], 0
	v_add3_u32 v250, v165, v198, v219
	ds_read_b128 v[242:245], v250
	s_waitcnt lgkmcnt(4)
	v_mfma_f32_16x16x32_bf16 v[222:225], v[194:197], v[80:83], v[222:225]
	v_add3_u32 v250, v165, v198, v220
	ds_read_b128 v[194:197], v250
	s_waitcnt lgkmcnt(4)
	v_mfma_f32_16x16x32_bf16 v[222:225], v[230:233], v[72:75], v[222:225]
	v_add3_u32 v250, v165, v198, v221
	ds_read_b128 v[230:233], v250
	s_waitcnt lgkmcnt(0)
	s_barrier
	v_mfma_f32_16x16x32_bf16 v[222:225], v[234:237], v[68:71], v[222:225]
	v_mfma_f32_16x16x32_bf16 v[222:225], v[238:241], v[64:67], v[222:225]
	v_mfma_f32_16x16x32_bf16 v[222:225], v[242:245], v[60:63], v[222:225]
	v_mfma_f32_16x16x32_bf16 v[222:225], v[194:197], v[56:59], v[222:225]
	v_mfma_f32_16x16x32_bf16 v[52:55], v[230:233], v[52:55], v[222:225]
	s_cbranch_vccz .LBB0_209
	s_add_i32 s26, s45, -3
	s_and_b64 s[20:21], s[42:43], exec
	s_cselect_b32 s30, s26, s48
	s_mov_b64 s[46:47], 0

; __device__ __forceinline__ void xcd_barrier(const XcdBarrier& b) {
;     asm volatile("s_waitcnt vmcnt(0)" ::: "memory");
;     __syncthreads();
;     if (threadIdx.x == 0) {
;         unsigned* bar = b.bar;
;         __builtin_amdgcn_s_waitcnt(0);
;         unsigned nloc = b.st[0], nx = b.st[1];
;         if (nloc == 0u) { xcd_barrier_complete(bar, b.x, nloc, nx); b.st[0] = nloc; b.st[1] = nx; }
; __global__ void __launch_bounds__(NTHREADS) mega(Args a) {
;     ...
;         if (ph + 1 < a.ph_hi) { if (ph == 0) cg::this_grid().sync(); else xcd_barrier(xbar); }
.LBB0_603:
	s_add_i32 s25, s90, 1
	s_cmp_ge_i32 s25, s91
	s_cbranch_scc1 .LBB0_7
	v_readlane_b32 s0, v254, 46
	v_readlane_b32 s1, v254, 47
	s_mov_b64 s[2:3], -1
	s_and_b64 vcc, exec, s[0:1]
	s_mov_b64 s[52:53], 0x8000
	s_mov_b64 s[68:69], 0x18000
	s_waitcnt vmcnt(0)
	v_readlane_b32 s0, v252, 2
	v_readlane_b32 s1, v252, 3
	s_waitcnt vmcnt(0) lgkmcnt(0)
	s_barrier
	s_and_saveexec_b64 s[2:3], s[0:1]
	s_cbranch_execz .LBB0_657
	s_add_i32 s36, 0, 0x24000
	v_mov_b32_e32 v0, s36
	s_waitcnt vmcnt(0) expcnt(0) lgkmcnt(0)
	ds_read_b32 v2, v0
	v_readlane_b32 s1, v253, 43
	s_waitcnt lgkmcnt(0)
	v_cmp_ne_u32_e32 vcc, 0, v2
	v_mov_b32_e32 v0, s1
	ds_read_b32 v0, v0
	s_cbranch_vccnz .LBB0_621
	s_load_dwordx2 s[20:21], s[60:61], 0x4
	s_mov_b32 s38, 1
	s_waitcnt lgkmcnt(0)
	s_mul_i32 s37, s20, s54
	s_mul_i32 s37, s37, s21
	s_branch .LBB0_609

; __device__ __forceinline__ void xcd_barrier(const XcdBarrier& b) {
;     ...
;     }
;     __syncthreads();
; }
; __global__ void __launch_bounds__(NTHREADS) mega(Args a) {
;     ...
;         if (ph + 1 < a.ph_hi) { if (ph == 0) cg::this_grid().sync(); else xcd_barrier(xbar); }
.LBB0_657:
	s_or_b64 exec, exec, s[2:3]
	s_waitcnt lgkmcnt(0)
	s_barrier
	s_branch .LBB0_8

; __global__ void __launch_bounds__(NTHREADS) mega(Args a) {
	.amdhsa_kernel _Z4mega4Args
		.amdhsa_group_segment_fixed_size 0
		.amdhsa_private_segment_fixed_size 0
		.amdhsa_kernarg_size 464
		.amdhsa_user_sgpr_count 2
		.amdhsa_user_sgpr_dispatch_ptr 0
		.amdhsa_user_sgpr_queue_ptr 0
		.amdhsa_user_sgpr_kernarg_segment_ptr 1
		.amdhsa_user_sgpr_dispatch_id 0
		.amdhsa_user_sgpr_kernarg_preload_length 0
		.amdhsa_user_sgpr_kernarg_preload_offset 0
		.amdhsa_user_sgpr_private_segment_size 0
		.amdhsa_uses_dynamic_stack 0
		.amdhsa_enable_private_segment 0
		.amdhsa_system_sgpr_workgroup_id_x 1
		.amdhsa_system_sgpr_workgroup_id_y 0
		.amdhsa_system_sgpr_workgroup_id_z 0
		.amdhsa_system_sgpr_workgroup_info 0
		.amdhsa_system_vgpr_workitem_id 2
		.amdhsa_next_free_vgpr 256
		.amdhsa_next_free_sgpr 100
		.amdhsa_accum_offset 256
		.amdhsa_reserve_vcc 1
		.amdhsa_float_round_mode_32 0
		.amdhsa_float_round_mode_16_64 0
		.amdhsa_float_denorm_mode_32 3
		.amdhsa_float_denorm_mode_16_64 3
		.amdhsa_dx10_clamp 1
		.amdhsa_ieee_mode 1
		.amdhsa_fp16_overflow 0
		.amdhsa_tg_split 0
		.amdhsa_exception_fp_ieee_invalid_op 0
		.amdhsa_exception_fp_denorm_src 0
		.amdhsa_exception_fp_ieee_div_zero 0
		.amdhsa_exception_fp_ieee_overflow 0
		.amdhsa_exception_fp_ieee_underflow 0
		.amdhsa_exception_fp_ieee_inexact 0
		.amdhsa_exception_int_div_zero 0
	.end_amdhsa_kernel

; __global__ void __launch_bounds__(NTHREADS) mega(Args a) {
amdhsa.kernels:
  - .agpr_count:     0
    .args:
      - .offset:         0
        .size:           208
        .value_kind:     by_value
      - .offset:         208
        .size:           4
        .value_kind:     hidden_block_count_x
      - .offset:         212
        .size:           4
        .value_kind:     hidden_block_count_y
      - .offset:         216
        .size:           4
        .value_kind:     hidden_block_count_z
      - .offset:         220
        .size:           2
        .value_kind:     hidden_group_size_x
      - .offset:         222
        .size:           2
        .value_kind:     hidden_group_size_y
      - .offset:         224
        .size:           2
        .value_kind:     hidden_group_size_z
      - .offset:         226
        .size:           2
        .value_kind:     hidden_remainder_x
      - .offset:         228
        .size:           2
        .value_kind:     hidden_remainder_y
      - .offset:         230
        .size:           2
        .value_kind:     hidden_remainder_z
      - .offset:         248
        .size:           8
        .value_kind:     hidden_global_offset_x
      - .offset:         256
        .size:           8
        .value_kind:     hidden_global_offset_y
      - .offset:         264
        .size:           8
        .value_kind:     hidden_global_offset_z
      - .offset:         272
        .size:           2
        .value_kind:     hidden_grid_dims
      - .offset:         296
        .size:           8
        .value_kind:     hidden_multigrid_sync_arg
      - .offset:         328
        .size:           4
        .value_kind:     hidden_dynamic_lds_size
    .group_segment_fixed_size: 0
    .kernarg_segment_align: 8
    .kernarg_segment_size: 464
    .language:       OpenCL C
    .language_version:
      - 2
      - 0
    .max_flat_workgroup_size: 512
    .name:           _Z4mega4Args
    .private_segment_fixed_size: 0
    .sgpr_count:     106
    .sgpr_spill_count: 258
    .symbol:         _Z4mega4Args.kd
    .uniform_work_group_size: 1
    .uses_dynamic_stack: false
    .vgpr_count:     256
    .vgpr_spill_count: 0
    .wavefront_size: 64
